# W_o / FFN2 unit header waits only for the tail's DMA (vmcnt(4)) instead of draining the epilogue's stores
# baseline (speedup 1.0000x reference)
.LBB0_127:
	v_mov_b32_e32 v67, v169
	s_mov_b32 s11, s8
	v_lshrrev_b32_e32 v69, 4, v67
	v_ashrrev_i32_e32 v71, 3, v67
	v_lshrrev_b32_e32 v77, 1, v67
	v_and_b32_e32 v80, 4, v69
	v_and_b32_e32 v81, 3, v71
	v_and_b32_e32 v73, 7, v67
	v_xor_b32_e32 v75, v71, v67
	v_and_b32_e32 v77, 16, v77
	v_and_b32_e32 v79, 8, v69
	v_or_b32_e32 v82, v80, v81
	v_lshlrev_b32_e32 v75, 4, v75
	v_or3_b32 v77, v77, v79, v82
	v_bitop3_b32 v79, v80, v73, v81 bitop3:0x36
	v_lshlrev_b32_e32 v71, 7, v71
	v_lshlrev_b32_e32 v79, 4, v79
	v_and_or_b32 v122, v75, s24, v71
	v_lshl_or_b32 v121, v77, 7, v79
	v_lshlrev_b32_e32 v34, 7, v67
	v_and_b32_e32 v35, 0x780, v34
	v_and_b32_e32 v123, 0x2780, v34
	v_bitop3_b32 v34, v69, v73, 3 bitop3:0x6c
	v_bfe_u32 v77, v67, 4, 2
	v_lshlrev_b32_e32 v124, 4, v34
	v_lshlrev_b32_e32 v34, 6, v67
	v_mov_b32_e32 v75, v1
	v_and_or_b32 v125, v34, s30, v35
	v_bitop3_b32 v34, v77, v73, 4 bitop3:0x36
	v_mov_b32_e32 v73, v1
	v_mov_b32_e32 v67, v1
	v_mov_b32_e32 v69, v1
	v_mov_b32_e32 v77, v1
	v_mov_b32_e32 v71, v1
	v_mov_b32_e32 v79, v1
	v_lshl_add_u64 v[100:101], v[74:75], 1, s[28:29]
	v_mov_b32_e32 v74, 0
	s_mov_b32 s5, s10
	s_mov_b32 s4, s9
	v_lshlrev_b32_e32 v126, 4, v34
	v_lshl_add_u64 v[98:99], v[72:73], 1, s[28:29]
	v_lshl_add_u64 v[102:103], v[76:77], 1, s[28:29]
	v_lshl_add_u64 v[104:105], v[78:79], 1, s[28:29]
	v_lshlrev_b64 v[106:107], 1, v[0:1]
	v_lshlrev_b64 v[108:109], 1, v[66:67]
	v_lshlrev_b64 v[110:111], 1, v[68:69]
	v_lshlrev_b64 v[112:113], 1, v[70:71]
	s_mov_b32 s8, -2
	s_mov_b64 s[42:43], s[72:73]
	v_mov_b32_e32 v75, v74
	v_mov_b32_e32 v76, v74
	v_mov_b32_e32 v77, v74
	v_mov_b32_e32 v62, v74
	v_mov_b32_e32 v63, v74
	v_mov_b32_e32 v64, v74
	v_mov_b32_e32 v65, v74
	v_mov_b32_e32 v66, v74
	v_mov_b32_e32 v67, v74
	v_mov_b32_e32 v68, v74
	v_mov_b32_e32 v69, v74
	v_mov_b32_e32 v58, v74
	v_mov_b32_e32 v59, v74
	v_mov_b32_e32 v60, v74
	v_mov_b32_e32 v61, v74
	v_mov_b32_e32 v70, v74
	v_mov_b32_e32 v71, v74
	v_mov_b32_e32 v72, v74
	v_mov_b32_e32 v73, v74
	v_mov_b32_e32 v54, v74
	v_mov_b32_e32 v55, v74
	v_mov_b32_e32 v56, v74
	v_mov_b32_e32 v57, v74
	v_mov_b32_e32 v78, v74
	v_mov_b32_e32 v79, v74
	v_mov_b32_e32 v80, v74
	v_mov_b32_e32 v81, v74
	v_mov_b32_e32 v50, v74
	v_mov_b32_e32 v51, v74
	v_mov_b32_e32 v52, v74
	v_mov_b32_e32 v53, v74
	v_mov_b32_e32 v82, v74
	v_mov_b32_e32 v83, v74
	v_mov_b32_e32 v84, v74
	v_mov_b32_e32 v85, v74
	v_mov_b32_e32 v46, v74
	v_mov_b32_e32 v47, v74
	v_mov_b32_e32 v48, v74
	v_mov_b32_e32 v49, v74
	v_mov_b32_e32 v86, v74
	v_mov_b32_e32 v87, v74
	v_mov_b32_e32 v88, v74
	v_mov_b32_e32 v89, v74
	v_mov_b32_e32 v42, v74
	v_mov_b32_e32 v43, v74
	v_mov_b32_e32 v44, v74
	v_mov_b32_e32 v45, v74
	v_mov_b32_e32 v90, v74
	v_mov_b32_e32 v91, v74
	v_mov_b32_e32 v92, v74
	v_mov_b32_e32 v93, v74
	v_mov_b32_e32 v38, v74
	v_mov_b32_e32 v39, v74
	v_mov_b32_e32 v40, v74
	v_mov_b32_e32 v41, v74
	v_mov_b32_e32 v94, v74
	v_mov_b32_e32 v95, v74
	v_mov_b32_e32 v96, v74
	v_mov_b32_e32 v97, v74
	v_mov_b32_e32 v34, v74
	v_mov_b32_e32 v35, v74
	v_mov_b32_e32 v36, v74
	v_mov_b32_e32 v37, v74
	s_waitcnt vmcnt(4)
	s_waitcnt lgkmcnt(0)
	s_barrier
	v_add_u32_e32 v127, v124, v123
	v_add_u32_e32 v129, v124, v125
	v_add_u32_e32 v128, v126, v125
	v_add_u32_e32 v130, v126, v123
	v_lshrrev_b32_e32 v218, 6, v169
	v_lshlrev_b32_e32 v218, 10, v218
	v_lshrrev_b32_e32 v219, 3, v169
	v_readfirstlane_b32 s100, v218
	v_and_b32_e32 v218, 3, v219
	v_bfe_u32 v220, v219, 4, 1
	v_lshl_or_b32 v218, v220, 2, v218
	v_bfe_u32 v220, v219, 2, 1
	v_lshl_or_b32 v218, v220, 3, v218
	v_bfe_u32 v220, v219, 3, 1
	v_lshl_or_b32 v218, v220, 4, v218
	v_sub_u32_e32 v218, v218, v219
	v_mul_i32_i24_e32 v218, 0x1600, v218
	v_and_b32_e32 v219, 7, v219
	v_lshlrev_b32_e32 v219, 4, v219
	v_add_u32_e32 v206, 0x7511000, v106
	v_xor_b32_e32 v194, v206, v219
	v_mov_b32_e32 v207, v98
	v_add_u32_e32 v195, v207, v218
	v_xor_b32_e32 v195, v195, v219
	v_add_u32_e32 v208, 0x7511000, v108
	v_xor_b32_e32 v196, v208, v219
	v_mov_b32_e32 v209, v100
	v_add_u32_e32 v197, v209, v218
	v_xor_b32_e32 v197, v197, v219
	v_add_u32_e32 v214, 0x7511000, v110
	v_xor_b32_e32 v202, v214, v219
	v_mov_b32_e32 v215, v102
	v_add_u32_e32 v203, v215, v218
	v_xor_b32_e32 v203, v203, v219
	v_add_u32_e32 v216, 0x7511000, v112
	v_xor_b32_e32 v204, v216, v219
	v_mov_b32_e32 v217, v104
	v_add_u32_e32 v205, v217, v218
	v_xor_b32_e32 v205, v205, v219

.LBB0_156:
	v_mov_b32_e32 v67, v169
	s_mov_b32 s11, s5
	v_lshrrev_b32_e32 v69, 4, v67
	v_ashrrev_i32_e32 v71, 3, v67
	v_lshrrev_b32_e32 v77, 1, v67
	v_and_b32_e32 v80, 4, v69
	v_and_b32_e32 v81, 3, v71
	v_and_b32_e32 v73, 7, v67
	v_xor_b32_e32 v75, v71, v67
	v_and_b32_e32 v77, 16, v77
	v_and_b32_e32 v79, 8, v69
	v_or_b32_e32 v82, v80, v81
	v_lshlrev_b32_e32 v75, 4, v75
	v_or3_b32 v77, v77, v79, v82
	v_bitop3_b32 v79, v80, v73, v81 bitop3:0x36
	v_lshlrev_b32_e32 v71, 7, v71
	v_lshlrev_b32_e32 v79, 4, v79
	v_and_or_b32 v117, v75, s24, v71
	v_lshl_or_b32 v116, v77, 7, v79
	v_lshlrev_b32_e32 v34, 7, v67
	v_and_b32_e32 v35, 0x780, v34
	v_and_b32_e32 v118, 0x2780, v34
	v_bitop3_b32 v34, v69, v73, 3 bitop3:0x6c
	v_bfe_u32 v77, v67, 4, 2
	v_lshlrev_b32_e32 v119, 4, v34
	v_lshlrev_b32_e32 v34, 6, v67
	v_mov_b32_e32 v75, v1
	v_and_or_b32 v120, v34, s30, v35
	v_bitop3_b32 v34, v77, v73, 4 bitop3:0x36
	v_mov_b32_e32 v73, v1
	v_mov_b32_e32 v67, v1
	v_mov_b32_e32 v69, v1
	v_mov_b32_e32 v77, v1
	v_mov_b32_e32 v71, v1
	v_mov_b32_e32 v79, v1
	v_lshl_add_u64 v[100:101], v[74:75], 1, s[28:29]
	v_mov_b32_e32 v74, 0
	s_mov_b32 s10, s9
	s_mov_b32 s4, s8
	v_lshlrev_b32_e32 v121, 4, v34
	v_lshl_add_u64 v[98:99], v[72:73], 1, s[28:29]
	v_lshl_add_u64 v[102:103], v[76:77], 1, s[28:29]
	v_lshl_add_u64 v[104:105], v[78:79], 1, s[28:29]
	v_lshlrev_b64 v[106:107], 1, v[0:1]
	v_lshlrev_b64 v[108:109], 1, v[66:67]
	v_lshlrev_b64 v[110:111], 1, v[68:69]
	v_lshlrev_b64 v[112:113], 1, v[70:71]
	s_mov_b32 s5, -2
	s_mov_b64 s[38:39], s[72:73]
	v_mov_b32_e32 v75, v74
	v_mov_b32_e32 v76, v74
	v_mov_b32_e32 v77, v74
	v_mov_b32_e32 v62, v74
	v_mov_b32_e32 v63, v74
	v_mov_b32_e32 v64, v74
	v_mov_b32_e32 v65, v74
	v_mov_b32_e32 v66, v74
	v_mov_b32_e32 v67, v74
	v_mov_b32_e32 v68, v74
	v_mov_b32_e32 v69, v74
	v_mov_b32_e32 v58, v74
	v_mov_b32_e32 v59, v74
	v_mov_b32_e32 v60, v74
	v_mov_b32_e32 v61, v74
	v_mov_b32_e32 v70, v74
	v_mov_b32_e32 v71, v74
	v_mov_b32_e32 v72, v74
	v_mov_b32_e32 v73, v74
	v_mov_b32_e32 v54, v74
	v_mov_b32_e32 v55, v74
	v_mov_b32_e32 v56, v74
	v_mov_b32_e32 v57, v74
	v_mov_b32_e32 v78, v74
	v_mov_b32_e32 v79, v74
	v_mov_b32_e32 v80, v74
	v_mov_b32_e32 v81, v74
	v_mov_b32_e32 v50, v74
	v_mov_b32_e32 v51, v74
	v_mov_b32_e32 v52, v74
	v_mov_b32_e32 v53, v74
	v_mov_b32_e32 v82, v74
	v_mov_b32_e32 v83, v74
	v_mov_b32_e32 v84, v74
	v_mov_b32_e32 v85, v74
	v_mov_b32_e32 v46, v74
	v_mov_b32_e32 v47, v74
	v_mov_b32_e32 v48, v74
	v_mov_b32_e32 v49, v74
	v_mov_b32_e32 v86, v74
	v_mov_b32_e32 v87, v74
	v_mov_b32_e32 v88, v74
	v_mov_b32_e32 v89, v74
	v_mov_b32_e32 v42, v74
	v_mov_b32_e32 v43, v74
	v_mov_b32_e32 v44, v74
	v_mov_b32_e32 v45, v74
	v_mov_b32_e32 v90, v74
	v_mov_b32_e32 v91, v74
	v_mov_b32_e32 v92, v74
	v_mov_b32_e32 v93, v74
	v_mov_b32_e32 v38, v74
	v_mov_b32_e32 v39, v74
	v_mov_b32_e32 v40, v74
	v_mov_b32_e32 v41, v74
	v_mov_b32_e32 v94, v74
	v_mov_b32_e32 v95, v74
	v_mov_b32_e32 v96, v74
	v_mov_b32_e32 v97, v74
	v_mov_b32_e32 v34, v74
	v_mov_b32_e32 v35, v74
	v_mov_b32_e32 v36, v74
	v_mov_b32_e32 v37, v74
	s_waitcnt vmcnt(4)
	s_waitcnt lgkmcnt(0)
	s_barrier
	v_lshrrev_b32_e32 v222, 6, v169
	v_lshlrev_b32_e32 v222, 10, v222
	v_lshrrev_b32_e32 v223, 3, v169
	v_readfirstlane_b32 s100, v222
	v_and_b32_e32 v222, 3, v223
	v_bfe_u32 v224, v223, 4, 1
	v_lshl_or_b32 v222, v224, 2, v222
	v_bfe_u32 v224, v223, 2, 1
	v_lshl_or_b32 v222, v224, 3, v222
	v_bfe_u32 v224, v223, 3, 1
	v_lshl_or_b32 v222, v224, 4, v222
	v_sub_u32_e32 v222, v222, v223
	v_mul_i32_i24_e32 v222, 0x800, v222
	v_and_b32_e32 v223, 7, v223
	v_lshlrev_b32_e32 v223, 4, v223
	v_add_u32_e32 v210, 0xef11000, v106
	v_xor_b32_e32 v194, v210, v223
	v_mov_b32_e32 v211, v98
	v_add_u32_e32 v195, v211, v222
	v_xor_b32_e32 v195, v195, v223
	v_add_u32_e32 v212, 0xef11000, v108
	v_xor_b32_e32 v196, v212, v223
	v_mov_b32_e32 v213, v100
	v_add_u32_e32 v197, v213, v222
	v_xor_b32_e32 v197, v197, v223
	v_add_u32_e32 v218, 0xef11000, v110
	v_xor_b32_e32 v202, v218, v223
	v_mov_b32_e32 v219, v102
	v_add_u32_e32 v203, v219, v222
	v_xor_b32_e32 v203, v203, v223
	v_add_u32_e32 v220, 0xef11000, v112
	v_xor_b32_e32 v204, v220, v223
	v_mov_b32_e32 v221, v104
	v_add_u32_e32 v205, v221, v222
	v_xor_b32_e32 v205, v205, v223
